# n9 plus write-through (sc0 sc1) SwiGLU activation stores in phases 3 and 11
# speedup vs baseline: 1.0358x; 1.0025x over previous
.LBB0_331:
	v_mul_f32_e32 v157, 0xbfb8aa3b, v124
	v_exp_f32_e32 v157, v157
	v_mul_f32_e32 v160, 0xbfb8aa3b, v125
	v_exp_f32_e32 v160, v160
	v_lshl_or_b32 v148, s37, 7, v152
	v_add_f32_e32 v157, 1.0, v157
	v_rcp_f32_e32 v157, v157
	v_add_f32_e32 v160, 1.0, v160
	v_rcp_f32_e32 v160, v160
	v_lshl_add_u32 v156, s58, 8, v150
	v_mul_f32_e32 v124, v124, v157
	v_mul_f32_e32 v116, v116, v124
	v_mul_f32_e32 v124, v125, v160
	v_mul_f32_e32 v125, 0xbfb8aa3b, v126
	v_exp_f32_e32 v125, v125
	v_mul_f32_e32 v157, 0xbfb8aa3b, v127
	v_exp_f32_e32 v157, v157
	v_mul_f32_e32 v117, v117, v124
	v_add_f32_e32 v124, 1.0, v125
	v_rcp_f32_e32 v124, v124
	v_add_f32_e32 v125, 1.0, v157
	v_rcp_f32_e32 v125, v125
	v_cvt_pk_bf16_f32 v116, v116, v117
	v_mul_f32_e32 v117, v126, v124
	v_mul_f32_e32 v124, 0xbfb8aa3b, v120
	v_exp_f32_e32 v124, v124
	v_mul_f32_e32 v117, v118, v117
	v_mul_f32_e32 v118, v127, v125
	v_mul_f32_e32 v125, 0xbfb8aa3b, v121
	v_exp_f32_e32 v125, v125
	v_mul_f32_e32 v118, v119, v118
	v_add_f32_e32 v119, 1.0, v124
	v_rcp_f32_e32 v119, v119
	v_add_f32_e32 v124, 1.0, v125
	v_rcp_f32_e32 v124, v124
	v_cvt_pk_bf16_f32 v117, v117, v118
	v_mul_f32_e32 v118, v120, v119
	v_mul_f32_e32 v119, 0xbfb8aa3b, v122
	v_exp_f32_e32 v119, v119
	v_mul_f32_e32 v120, 0xbfb8aa3b, v123
	v_exp_f32_e32 v120, v120
	v_mul_f32_e32 v112, v112, v118
	v_mul_f32_e32 v118, v121, v124
	v_mul_f32_e32 v113, v113, v118
	v_add_f32_e32 v118, 1.0, v119
	v_rcp_f32_e32 v119, v118
	v_add_f32_e32 v118, 1.0, v120
	v_rcp_f32_e32 v120, v118
	v_cvt_pk_bf16_f32 v118, v112, v113
	v_mul_f32_e32 v112, v122, v119
	v_mul_f32_e32 v112, v114, v112
	v_mul_f32_e32 v113, v123, v120
	v_mul_f32_e32 v113, v115, v113
	v_cvt_pk_bf16_f32 v119, v112, v113
	v_mul_f32_e32 v113, 0xbfb8aa3b, v108
	v_exp_f32_e32 v114, v113
	v_mul_f32_e32 v113, 0xbfb8aa3b, v109
	v_exp_f32_e32 v115, v113
	v_ashrrev_i32_e32 v149, 31, v148
	v_add_f32_e32 v114, 1.0, v114
	v_rcp_f32_e32 v114, v114
	v_add_f32_e32 v115, 1.0, v115
	v_rcp_f32_e32 v115, v115
	v_mov_b64_e32 v[146:147], s[18:19]
	v_mul_f32_e32 v108, v108, v114
	v_mul_f32_e32 v100, v100, v108
	v_mul_f32_e32 v108, v109, v115
	v_mul_f32_e32 v109, 0xbfb8aa3b, v110
	v_exp_f32_e32 v109, v109
	v_mul_f32_e32 v114, 0xbfb8aa3b, v111
	v_exp_f32_e32 v114, v114
	v_mul_f32_e32 v101, v101, v108
	v_add_f32_e32 v108, 1.0, v109
	v_rcp_f32_e32 v108, v108
	v_mad_i64_i32 v[158:159], s[6:7], v156, s36, v[146:147]
	v_lshlrev_b64 v[148:149], 1, v[148:149]
	v_lshl_add_u64 v[158:159], v[158:159], 0, v[148:149]
	v_add_f32_e32 v109, 1.0, v114
	global_store_dwordx4 v[158:159], v[116:119], off sc0 sc1
	v_rcp_f32_e32 v109, v109
	v_cvt_pk_bf16_f32 v100, v100, v101
	v_mul_f32_e32 v101, v110, v108
	v_mul_f32_e32 v108, 0xbfb8aa3b, v104
	v_exp_f32_e32 v108, v108
	v_mul_f32_e32 v101, v102, v101
	v_mul_f32_e32 v102, v111, v109
	v_mul_f32_e32 v109, 0xbfb8aa3b, v105
	v_exp_f32_e32 v109, v109
	v_mul_f32_e32 v102, v103, v102
	v_add_f32_e32 v103, 1.0, v108
	v_rcp_f32_e32 v103, v103
	v_add_f32_e32 v108, 1.0, v109
	v_rcp_f32_e32 v108, v108
	v_cvt_pk_bf16_f32 v101, v101, v102
	v_mul_f32_e32 v102, v104, v103
	v_mul_f32_e32 v103, 0xbfb8aa3b, v106
	v_exp_f32_e32 v103, v103
	v_mul_f32_e32 v104, 0xbfb8aa3b, v107
	v_exp_f32_e32 v104, v104
	v_mul_f32_e32 v96, v96, v102
	v_mul_f32_e32 v102, v105, v108
	v_mul_f32_e32 v97, v97, v102
	v_add_f32_e32 v102, 1.0, v103
	v_rcp_f32_e32 v103, v102
	v_add_f32_e32 v102, 1.0, v104
	v_rcp_f32_e32 v104, v102
	v_cvt_pk_bf16_f32 v102, v96, v97
	v_mul_f32_e32 v96, v106, v103
	v_mul_f32_e32 v96, v98, v96
	v_mul_f32_e32 v97, v107, v104
	v_mul_f32_e32 v97, v99, v97
	v_cvt_pk_bf16_f32 v103, v96, v97
	v_mul_f32_e32 v97, 0xbfb8aa3b, v92
	v_exp_f32_e32 v98, v97
	v_mul_f32_e32 v97, 0xbfb8aa3b, v93
	v_exp_f32_e32 v99, v97
	v_or_b32_e32 v112, 16, v156
	v_add_f32_e32 v98, 1.0, v98
	v_rcp_f32_e32 v98, v98
	v_add_f32_e32 v99, 1.0, v99
	v_rcp_f32_e32 v99, v99
	v_mad_i64_i32 v[112:113], s[6:7], v112, s36, v[146:147]
	v_mul_f32_e32 v92, v92, v98
	v_mul_f32_e32 v84, v84, v92
	v_mul_f32_e32 v92, v93, v99
	v_mul_f32_e32 v93, 0xbfb8aa3b, v94
	v_exp_f32_e32 v93, v93
	v_mul_f32_e32 v98, 0xbfb8aa3b, v95
	v_exp_f32_e32 v98, v98
	v_mul_f32_e32 v85, v85, v92
	v_add_f32_e32 v92, 1.0, v93
	v_rcp_f32_e32 v92, v92
	v_lshl_add_u64 v[112:113], v[112:113], 0, v[148:149]
	v_add_f32_e32 v93, 1.0, v98
	global_store_dwordx4 v[112:113], v[100:103], off sc0 sc1
	v_rcp_f32_e32 v93, v93
	v_cvt_pk_bf16_f32 v84, v84, v85
	v_mul_f32_e32 v85, v94, v92
	v_mul_f32_e32 v92, 0xbfb8aa3b, v88
	v_exp_f32_e32 v92, v92
	v_mul_f32_e32 v85, v86, v85
	v_mul_f32_e32 v86, v95, v93
	v_mul_f32_e32 v93, 0xbfb8aa3b, v89
	v_exp_f32_e32 v93, v93
	v_mul_f32_e32 v86, v87, v86
	v_add_f32_e32 v87, 1.0, v92
	v_rcp_f32_e32 v87, v87
	v_add_f32_e32 v92, 1.0, v93
	v_rcp_f32_e32 v92, v92
	v_cvt_pk_bf16_f32 v85, v85, v86
	v_mul_f32_e32 v86, v88, v87
	v_mul_f32_e32 v87, 0xbfb8aa3b, v90
	v_exp_f32_e32 v87, v87
	v_mul_f32_e32 v88, 0xbfb8aa3b, v91
	v_exp_f32_e32 v88, v88
	v_mul_f32_e32 v80, v80, v86
	v_mul_f32_e32 v86, v89, v92
	v_mul_f32_e32 v81, v81, v86
	v_add_f32_e32 v86, 1.0, v87
	v_rcp_f32_e32 v87, v86
	v_add_f32_e32 v86, 1.0, v88
	v_rcp_f32_e32 v88, v86
	v_cvt_pk_bf16_f32 v86, v80, v81
	v_mul_f32_e32 v80, v90, v87
	v_mul_f32_e32 v80, v82, v80
	v_mul_f32_e32 v81, v91, v88
	v_mul_f32_e32 v81, v83, v81
	v_cvt_pk_bf16_f32 v87, v80, v81
	v_mul_f32_e32 v81, 0xbfb8aa3b, v76
	v_exp_f32_e32 v82, v81
	v_mul_f32_e32 v81, 0xbfb8aa3b, v77
	v_exp_f32_e32 v83, v81
	v_or_b32_e32 v96, 32, v156
	v_add_f32_e32 v82, 1.0, v82
	v_rcp_f32_e32 v82, v82
	v_add_f32_e32 v83, 1.0, v83
	v_rcp_f32_e32 v83, v83
	v_mad_i64_i32 v[96:97], s[6:7], v96, s36, v[146:147]
	v_mul_f32_e32 v76, v76, v82
	v_mul_f32_e32 v68, v68, v76
	v_mul_f32_e32 v76, v77, v83
	v_mul_f32_e32 v77, 0xbfb8aa3b, v78
	v_exp_f32_e32 v77, v77
	v_mul_f32_e32 v82, 0xbfb8aa3b, v79
	v_exp_f32_e32 v82, v82
	v_mul_f32_e32 v69, v69, v76
	v_add_f32_e32 v76, 1.0, v77
	v_rcp_f32_e32 v76, v76
	v_lshl_add_u64 v[96:97], v[96:97], 0, v[148:149]
	v_add_f32_e32 v77, 1.0, v82
	global_store_dwordx4 v[96:97], v[84:87], off sc0 sc1
	v_rcp_f32_e32 v77, v77
	v_cvt_pk_bf16_f32 v68, v68, v69
	v_mul_f32_e32 v69, v78, v76
	v_mul_f32_e32 v76, 0xbfb8aa3b, v72
	v_exp_f32_e32 v76, v76
	v_mul_f32_e32 v69, v70, v69
	v_mul_f32_e32 v70, v79, v77
	v_mul_f32_e32 v77, 0xbfb8aa3b, v73
	v_exp_f32_e32 v77, v77
	v_mul_f32_e32 v70, v71, v70
	v_add_f32_e32 v71, 1.0, v76
	v_rcp_f32_e32 v71, v71
	v_add_f32_e32 v76, 1.0, v77
	v_rcp_f32_e32 v76, v76
	v_cvt_pk_bf16_f32 v69, v69, v70
	v_mul_f32_e32 v70, v72, v71
	v_mul_f32_e32 v71, 0xbfb8aa3b, v74
	v_exp_f32_e32 v71, v71
	v_mul_f32_e32 v72, 0xbfb8aa3b, v75
	v_exp_f32_e32 v72, v72
	v_mul_f32_e32 v64, v64, v70
	v_mul_f32_e32 v70, v73, v76
	v_mul_f32_e32 v65, v65, v70
	v_add_f32_e32 v70, 1.0, v71
	v_rcp_f32_e32 v71, v70
	v_add_f32_e32 v70, 1.0, v72
	v_rcp_f32_e32 v72, v70
	v_cvt_pk_bf16_f32 v70, v64, v65
	v_mul_f32_e32 v64, v74, v71
	v_mul_f32_e32 v64, v66, v64
	v_mul_f32_e32 v65, v75, v72
	v_mul_f32_e32 v65, v67, v65
	v_cvt_pk_bf16_f32 v71, v64, v65
	v_mul_f32_e32 v65, 0xbfb8aa3b, v60
	v_exp_f32_e32 v66, v65
	v_mul_f32_e32 v65, 0xbfb8aa3b, v61
	v_exp_f32_e32 v67, v65
	v_or_b32_e32 v80, 48, v156
	v_add_f32_e32 v66, 1.0, v66
	v_rcp_f32_e32 v66, v66
	v_add_f32_e32 v67, 1.0, v67
	v_rcp_f32_e32 v67, v67
	v_mad_i64_i32 v[80:81], s[6:7], v80, s36, v[146:147]
	v_mul_f32_e32 v60, v60, v66
	v_mul_f32_e32 v52, v52, v60
	v_mul_f32_e32 v60, v61, v67
	v_mul_f32_e32 v61, 0xbfb8aa3b, v62
	v_exp_f32_e32 v61, v61
	v_mul_f32_e32 v66, 0xbfb8aa3b, v63
	v_exp_f32_e32 v66, v66
	v_mul_f32_e32 v53, v53, v60
	v_add_f32_e32 v60, 1.0, v61
	v_rcp_f32_e32 v60, v60
	v_lshl_add_u64 v[80:81], v[80:81], 0, v[148:149]
	v_add_f32_e32 v61, 1.0, v66
	global_store_dwordx4 v[80:81], v[68:71], off sc0 sc1
	v_rcp_f32_e32 v61, v61
	v_cvt_pk_bf16_f32 v52, v52, v53
	v_mul_f32_e32 v53, v62, v60
	v_mul_f32_e32 v60, 0xbfb8aa3b, v56
	v_exp_f32_e32 v60, v60
	v_mul_f32_e32 v53, v54, v53
	v_mul_f32_e32 v54, v63, v61
	v_mul_f32_e32 v61, 0xbfb8aa3b, v57
	v_exp_f32_e32 v61, v61
	v_mul_f32_e32 v54, v55, v54
	v_add_f32_e32 v55, 1.0, v60
	v_rcp_f32_e32 v55, v55
	v_add_f32_e32 v60, 1.0, v61
	v_rcp_f32_e32 v60, v60
	v_cvt_pk_bf16_f32 v53, v53, v54
	v_mul_f32_e32 v54, v56, v55
	v_mul_f32_e32 v55, 0xbfb8aa3b, v58
	v_exp_f32_e32 v55, v55
	v_mul_f32_e32 v56, 0xbfb8aa3b, v59
	v_exp_f32_e32 v56, v56
	v_mul_f32_e32 v48, v48, v54
	v_mul_f32_e32 v54, v57, v60
	v_mul_f32_e32 v49, v49, v54
	v_add_f32_e32 v54, 1.0, v55
	v_rcp_f32_e32 v55, v54
	v_add_f32_e32 v54, 1.0, v56
	v_rcp_f32_e32 v56, v54
	v_cvt_pk_bf16_f32 v54, v48, v49
	v_mul_f32_e32 v48, v58, v55
	v_mul_f32_e32 v48, v50, v48
	v_mul_f32_e32 v49, v59, v56
	v_mul_f32_e32 v49, v51, v49
	v_cvt_pk_bf16_f32 v55, v48, v49
	v_mul_f32_e32 v49, 0xbfb8aa3b, v44
	v_exp_f32_e32 v50, v49
	v_mul_f32_e32 v49, 0xbfb8aa3b, v45
	v_exp_f32_e32 v51, v49
	v_add_u32_e32 v64, 0x80, v156
	v_add_f32_e32 v50, 1.0, v50
	v_rcp_f32_e32 v50, v50
	v_add_f32_e32 v51, 1.0, v51
	v_rcp_f32_e32 v51, v51
	v_mad_i64_i32 v[64:65], s[6:7], v64, s36, v[146:147]
	v_mul_f32_e32 v44, v44, v50
	v_mul_f32_e32 v36, v36, v44
	v_mul_f32_e32 v44, v45, v51
	v_mul_f32_e32 v45, 0xbfb8aa3b, v46
	v_exp_f32_e32 v45, v45
	v_mul_f32_e32 v50, 0xbfb8aa3b, v47
	v_exp_f32_e32 v50, v50
	v_mul_f32_e32 v37, v37, v44
	v_add_f32_e32 v44, 1.0, v45
	v_rcp_f32_e32 v44, v44
	v_lshl_add_u64 v[64:65], v[64:65], 0, v[148:149]
	v_add_f32_e32 v45, 1.0, v50
	global_store_dwordx4 v[64:65], v[52:55], off sc0 sc1
	v_rcp_f32_e32 v45, v45
	v_cvt_pk_bf16_f32 v36, v36, v37
	v_mul_f32_e32 v37, v46, v44
	v_mul_f32_e32 v44, 0xbfb8aa3b, v40
	v_exp_f32_e32 v44, v44
	v_mul_f32_e32 v37, v38, v37
	v_mul_f32_e32 v38, v47, v45
	v_mul_f32_e32 v45, 0xbfb8aa3b, v41
	v_exp_f32_e32 v45, v45
	v_mul_f32_e32 v38, v39, v38
	v_add_f32_e32 v39, 1.0, v44
	v_rcp_f32_e32 v39, v39
	v_add_f32_e32 v44, 1.0, v45
	v_rcp_f32_e32 v44, v44
	v_cvt_pk_bf16_f32 v37, v37, v38
	v_mul_f32_e32 v38, v40, v39
	v_mul_f32_e32 v39, 0xbfb8aa3b, v42
	v_exp_f32_e32 v39, v39
	v_mul_f32_e32 v40, 0xbfb8aa3b, v43
	v_exp_f32_e32 v40, v40
	v_mul_f32_e32 v32, v32, v38
	v_mul_f32_e32 v38, v41, v44
	v_mul_f32_e32 v33, v33, v38
	v_add_f32_e32 v38, 1.0, v39
	v_rcp_f32_e32 v39, v38
	v_add_f32_e32 v38, 1.0, v40
	v_rcp_f32_e32 v40, v38
	v_cvt_pk_bf16_f32 v38, v32, v33
	v_mul_f32_e32 v32, v42, v39
	v_mul_f32_e32 v32, v34, v32
	v_mul_f32_e32 v33, v43, v40
	v_mul_f32_e32 v33, v35, v33
	v_cvt_pk_bf16_f32 v39, v32, v33
	v_mul_f32_e32 v33, 0xbfb8aa3b, v28
	v_exp_f32_e32 v34, v33
	v_mul_f32_e32 v33, 0xbfb8aa3b, v29
	v_exp_f32_e32 v35, v33
	v_add_u32_e32 v48, 0x90, v156
	v_add_f32_e32 v34, 1.0, v34
	v_rcp_f32_e32 v34, v34
	v_add_f32_e32 v35, 1.0, v35
	v_rcp_f32_e32 v35, v35
	v_mad_i64_i32 v[48:49], s[6:7], v48, s36, v[146:147]
	v_mul_f32_e32 v28, v28, v34
	v_mul_f32_e32 v20, v20, v28
	v_mul_f32_e32 v28, v29, v35
	v_mul_f32_e32 v29, 0xbfb8aa3b, v30
	v_exp_f32_e32 v29, v29
	v_mul_f32_e32 v34, 0xbfb8aa3b, v31
	v_exp_f32_e32 v34, v34
	v_mul_f32_e32 v21, v21, v28
	v_add_f32_e32 v28, 1.0, v29
	v_rcp_f32_e32 v28, v28
	v_lshl_add_u64 v[48:49], v[48:49], 0, v[148:149]
	v_add_f32_e32 v29, 1.0, v34
	global_store_dwordx4 v[48:49], v[36:39], off sc0 sc1
	v_rcp_f32_e32 v29, v29
	v_cvt_pk_bf16_f32 v20, v20, v21
	v_mul_f32_e32 v21, v30, v28
	v_mul_f32_e32 v28, 0xbfb8aa3b, v24
	v_exp_f32_e32 v28, v28
	v_mul_f32_e32 v21, v22, v21
	v_mul_f32_e32 v22, v31, v29
	v_mul_f32_e32 v29, 0xbfb8aa3b, v25
	v_exp_f32_e32 v29, v29
	v_mul_f32_e32 v22, v23, v22
	v_add_f32_e32 v23, 1.0, v28
	v_rcp_f32_e32 v23, v23
	v_add_f32_e32 v28, 1.0, v29
	v_rcp_f32_e32 v28, v28
	v_cvt_pk_bf16_f32 v21, v21, v22
	v_mul_f32_e32 v22, v24, v23
	v_mul_f32_e32 v23, 0xbfb8aa3b, v26
	v_exp_f32_e32 v23, v23
	v_mul_f32_e32 v24, 0xbfb8aa3b, v27
	v_exp_f32_e32 v24, v24
	v_mul_f32_e32 v16, v16, v22
	v_mul_f32_e32 v22, v25, v28
	v_mul_f32_e32 v17, v17, v22
	v_add_f32_e32 v22, 1.0, v23
	v_rcp_f32_e32 v23, v22
	v_add_f32_e32 v22, 1.0, v24
	v_rcp_f32_e32 v24, v22
	v_cvt_pk_bf16_f32 v22, v16, v17
	v_mul_f32_e32 v16, v26, v23
	v_mul_f32_e32 v16, v18, v16
	v_mul_f32_e32 v17, v27, v24
	v_mul_f32_e32 v17, v19, v17
	v_cvt_pk_bf16_f32 v23, v16, v17
	v_mul_f32_e32 v17, 0xbfb8aa3b, v12
	v_exp_f32_e32 v18, v17
	v_mul_f32_e32 v17, 0xbfb8aa3b, v13
	v_exp_f32_e32 v19, v17
	v_add_u32_e32 v32, 0xa0, v156
	v_add_f32_e32 v18, 1.0, v18
	v_rcp_f32_e32 v18, v18
	v_add_f32_e32 v19, 1.0, v19
	v_rcp_f32_e32 v19, v19
	v_mad_i64_i32 v[32:33], s[6:7], v32, s36, v[146:147]
	v_mul_f32_e32 v12, v12, v18
	v_mul_f32_e32 v4, v4, v12
	v_mul_f32_e32 v12, v13, v19
	v_mul_f32_e32 v13, 0xbfb8aa3b, v14
	v_exp_f32_e32 v13, v13
	v_mul_f32_e32 v18, 0xbfb8aa3b, v15
	v_exp_f32_e32 v18, v18
	v_mul_f32_e32 v5, v5, v12
	v_add_f32_e32 v12, 1.0, v13
	v_rcp_f32_e32 v12, v12
	v_lshl_add_u64 v[32:33], v[32:33], 0, v[148:149]
	v_add_f32_e32 v13, 1.0, v18
	global_store_dwordx4 v[32:33], v[20:23], off sc0 sc1
	v_rcp_f32_e32 v13, v13
	v_cvt_pk_bf16_f32 v4, v4, v5
	v_mul_f32_e32 v5, v14, v12
	v_mul_f32_e32 v12, 0xbfb8aa3b, v8
	v_exp_f32_e32 v12, v12
	v_mul_f32_e32 v5, v6, v5
	v_mul_f32_e32 v6, v15, v13
	v_mul_f32_e32 v13, 0xbfb8aa3b, v9
	v_exp_f32_e32 v13, v13
	v_mul_f32_e32 v6, v7, v6
	v_add_f32_e32 v7, 1.0, v12
	v_rcp_f32_e32 v7, v7
	v_add_f32_e32 v12, 1.0, v13
	v_rcp_f32_e32 v12, v12
	v_cvt_pk_bf16_f32 v5, v5, v6
	v_mul_f32_e32 v6, v8, v7
	v_mul_f32_e32 v7, 0xbfb8aa3b, v10
	v_exp_f32_e32 v7, v7
	v_mul_f32_e32 v8, 0xbfb8aa3b, v11
	v_exp_f32_e32 v8, v8
	v_mul_f32_e32 v0, v0, v6
	v_mul_f32_e32 v6, v9, v12
	v_mul_f32_e32 v1, v1, v6
	v_add_f32_e32 v6, 1.0, v7
	v_rcp_f32_e32 v7, v6
	v_add_f32_e32 v6, 1.0, v8
	v_rcp_f32_e32 v8, v6
	v_add_u32_e32 v16, 0xb0, v156
	v_mad_i64_i32 v[16:17], s[6:7], v16, s36, v[146:147]
	v_lshl_add_u64 v[16:17], v[16:17], 0, v[148:149]
	v_cvt_pk_bf16_f32 v6, v0, v1
	v_mul_f32_e32 v0, v10, v7
	v_mul_f32_e32 v1, v11, v8
	s_andn2_b64 vcc, exec, s[0:1]
	s_mov_b64 s[0:1], -1
	v_mul_f32_e32 v0, v2, v0
	v_mul_f32_e32 v1, v3, v1
	v_cvt_pk_bf16_f32 v7, v0, v1
	global_store_dwordx4 v[16:17], v[4:7], off sc0 sc1
	s_cbranch_vccnz .LBB0_320
	s_andn2_b64 vcc, exec, s[22:23]
	s_cbranch_vccnz .LBB0_319
	s_barrier
	s_branch .LBB0_319

.LBB0_1226:
	v_mul_f32_e32 v157, 0xbfb8aa3b, v124
	v_exp_f32_e32 v157, v157
	v_mul_f32_e32 v160, 0xbfb8aa3b, v125
	v_exp_f32_e32 v160, v160
	v_lshl_or_b32 v148, s54, 7, v152
	v_add_f32_e32 v157, 1.0, v157
	v_rcp_f32_e32 v157, v157
	v_add_f32_e32 v160, 1.0, v160
	v_rcp_f32_e32 v160, v160
	v_lshl_add_u32 v156, s36, 8, v150
	v_mul_f32_e32 v124, v124, v157
	v_mul_f32_e32 v116, v116, v124
	v_mul_f32_e32 v124, v125, v160
	v_mul_f32_e32 v125, 0xbfb8aa3b, v126
	v_exp_f32_e32 v125, v125
	v_mul_f32_e32 v157, 0xbfb8aa3b, v127
	v_exp_f32_e32 v157, v157
	v_mul_f32_e32 v117, v117, v124
	v_add_f32_e32 v124, 1.0, v125
	v_rcp_f32_e32 v124, v124
	v_add_f32_e32 v125, 1.0, v157
	v_rcp_f32_e32 v125, v125
	v_cvt_pk_bf16_f32 v116, v116, v117
	v_mul_f32_e32 v117, v126, v124
	v_mul_f32_e32 v124, 0xbfb8aa3b, v120
	v_exp_f32_e32 v124, v124
	v_mul_f32_e32 v117, v118, v117
	v_mul_f32_e32 v118, v127, v125
	v_mul_f32_e32 v125, 0xbfb8aa3b, v121
	v_exp_f32_e32 v125, v125
	v_mul_f32_e32 v118, v119, v118
	v_add_f32_e32 v119, 1.0, v124
	v_rcp_f32_e32 v119, v119
	v_add_f32_e32 v124, 1.0, v125
	v_rcp_f32_e32 v124, v124
	v_cvt_pk_bf16_f32 v117, v117, v118
	v_mul_f32_e32 v118, v120, v119
	v_mul_f32_e32 v119, 0xbfb8aa3b, v122
	v_exp_f32_e32 v119, v119
	v_mul_f32_e32 v120, 0xbfb8aa3b, v123
	v_exp_f32_e32 v120, v120
	v_mul_f32_e32 v112, v112, v118
	v_mul_f32_e32 v118, v121, v124
	v_mul_f32_e32 v113, v113, v118
	v_add_f32_e32 v118, 1.0, v119
	v_rcp_f32_e32 v119, v118
	v_add_f32_e32 v118, 1.0, v120
	v_rcp_f32_e32 v120, v118
	v_cvt_pk_bf16_f32 v118, v112, v113
	v_mul_f32_e32 v112, v122, v119
	v_mul_f32_e32 v112, v114, v112
	v_mul_f32_e32 v113, v123, v120
	v_mul_f32_e32 v113, v115, v113
	v_cvt_pk_bf16_f32 v119, v112, v113
	v_mul_f32_e32 v113, 0xbfb8aa3b, v108
	v_exp_f32_e32 v114, v113
	v_mul_f32_e32 v113, 0xbfb8aa3b, v109
	v_exp_f32_e32 v115, v113
	v_ashrrev_i32_e32 v149, 31, v148
	v_add_f32_e32 v114, 1.0, v114
	v_rcp_f32_e32 v114, v114
	v_add_f32_e32 v115, 1.0, v115
	v_rcp_f32_e32 v115, v115
	v_mov_b64_e32 v[146:147], s[18:19]
	v_mul_f32_e32 v108, v108, v114
	v_mul_f32_e32 v100, v100, v108
	v_mul_f32_e32 v108, v109, v115
	v_mul_f32_e32 v109, 0xbfb8aa3b, v110
	v_exp_f32_e32 v109, v109
	v_mul_f32_e32 v114, 0xbfb8aa3b, v111
	v_exp_f32_e32 v114, v114
	v_mul_f32_e32 v101, v101, v108
	v_add_f32_e32 v108, 1.0, v109
	v_rcp_f32_e32 v108, v108
	v_mad_i64_i32 v[158:159], s[6:7], v156, s53, v[146:147]
	v_lshlrev_b64 v[148:149], 1, v[148:149]
	v_lshl_add_u64 v[158:159], v[158:159], 0, v[148:149]
	v_add_f32_e32 v109, 1.0, v114
	global_store_dwordx4 v[158:159], v[116:119], off sc0 sc1
	v_rcp_f32_e32 v109, v109
	v_cvt_pk_bf16_f32 v100, v100, v101
	v_mul_f32_e32 v101, v110, v108
	v_mul_f32_e32 v108, 0xbfb8aa3b, v104
	v_exp_f32_e32 v108, v108
	v_mul_f32_e32 v101, v102, v101
	v_mul_f32_e32 v102, v111, v109
	v_mul_f32_e32 v109, 0xbfb8aa3b, v105
	v_exp_f32_e32 v109, v109
	v_mul_f32_e32 v102, v103, v102
	v_add_f32_e32 v103, 1.0, v108
	v_rcp_f32_e32 v103, v103
	v_add_f32_e32 v108, 1.0, v109
	v_rcp_f32_e32 v108, v108
	v_cvt_pk_bf16_f32 v101, v101, v102
	v_mul_f32_e32 v102, v104, v103
	v_mul_f32_e32 v103, 0xbfb8aa3b, v106
	v_exp_f32_e32 v103, v103
	v_mul_f32_e32 v104, 0xbfb8aa3b, v107
	v_exp_f32_e32 v104, v104
	v_mul_f32_e32 v96, v96, v102
	v_mul_f32_e32 v102, v105, v108
	v_mul_f32_e32 v97, v97, v102
	v_add_f32_e32 v102, 1.0, v103
	v_rcp_f32_e32 v103, v102
	v_add_f32_e32 v102, 1.0, v104
	v_rcp_f32_e32 v104, v102
	v_cvt_pk_bf16_f32 v102, v96, v97
	v_mul_f32_e32 v96, v106, v103
	v_mul_f32_e32 v96, v98, v96
	v_mul_f32_e32 v97, v107, v104
	v_mul_f32_e32 v97, v99, v97
	v_cvt_pk_bf16_f32 v103, v96, v97
	v_mul_f32_e32 v97, 0xbfb8aa3b, v92
	v_exp_f32_e32 v98, v97
	v_mul_f32_e32 v97, 0xbfb8aa3b, v93
	v_exp_f32_e32 v99, v97
	v_or_b32_e32 v112, 16, v156
	v_add_f32_e32 v98, 1.0, v98
	v_rcp_f32_e32 v98, v98
	v_add_f32_e32 v99, 1.0, v99
	v_rcp_f32_e32 v99, v99
	v_mad_i64_i32 v[112:113], s[6:7], v112, s53, v[146:147]
	v_mul_f32_e32 v92, v92, v98
	v_mul_f32_e32 v84, v84, v92
	v_mul_f32_e32 v92, v93, v99
	v_mul_f32_e32 v93, 0xbfb8aa3b, v94
	v_exp_f32_e32 v93, v93
	v_mul_f32_e32 v98, 0xbfb8aa3b, v95
	v_exp_f32_e32 v98, v98
	v_mul_f32_e32 v85, v85, v92
	v_add_f32_e32 v92, 1.0, v93
	v_rcp_f32_e32 v92, v92
	v_lshl_add_u64 v[112:113], v[112:113], 0, v[148:149]
	v_add_f32_e32 v93, 1.0, v98
	global_store_dwordx4 v[112:113], v[100:103], off sc0 sc1
	v_rcp_f32_e32 v93, v93
	v_cvt_pk_bf16_f32 v84, v84, v85
	v_mul_f32_e32 v85, v94, v92
	v_mul_f32_e32 v92, 0xbfb8aa3b, v88
	v_exp_f32_e32 v92, v92
	v_mul_f32_e32 v85, v86, v85
	v_mul_f32_e32 v86, v95, v93
	v_mul_f32_e32 v93, 0xbfb8aa3b, v89
	v_exp_f32_e32 v93, v93
	v_mul_f32_e32 v86, v87, v86
	v_add_f32_e32 v87, 1.0, v92
	v_rcp_f32_e32 v87, v87
	v_add_f32_e32 v92, 1.0, v93
	v_rcp_f32_e32 v92, v92
	v_cvt_pk_bf16_f32 v85, v85, v86
	v_mul_f32_e32 v86, v88, v87
	v_mul_f32_e32 v87, 0xbfb8aa3b, v90
	v_exp_f32_e32 v87, v87
	v_mul_f32_e32 v88, 0xbfb8aa3b, v91
	v_exp_f32_e32 v88, v88
	v_mul_f32_e32 v80, v80, v86
	v_mul_f32_e32 v86, v89, v92
	v_mul_f32_e32 v81, v81, v86
	v_add_f32_e32 v86, 1.0, v87
	v_rcp_f32_e32 v87, v86
	v_add_f32_e32 v86, 1.0, v88
	v_rcp_f32_e32 v88, v86
	v_cvt_pk_bf16_f32 v86, v80, v81
	v_mul_f32_e32 v80, v90, v87
	v_mul_f32_e32 v80, v82, v80
	v_mul_f32_e32 v81, v91, v88
	v_mul_f32_e32 v81, v83, v81
	v_cvt_pk_bf16_f32 v87, v80, v81
	v_mul_f32_e32 v81, 0xbfb8aa3b, v76
	v_exp_f32_e32 v82, v81
	v_mul_f32_e32 v81, 0xbfb8aa3b, v77
	v_exp_f32_e32 v83, v81
	v_or_b32_e32 v96, 32, v156
	v_add_f32_e32 v82, 1.0, v82
	v_rcp_f32_e32 v82, v82
	v_add_f32_e32 v83, 1.0, v83
	v_rcp_f32_e32 v83, v83
	v_mad_i64_i32 v[96:97], s[6:7], v96, s53, v[146:147]
	v_mul_f32_e32 v76, v76, v82
	v_mul_f32_e32 v68, v68, v76
	v_mul_f32_e32 v76, v77, v83
	v_mul_f32_e32 v77, 0xbfb8aa3b, v78
	v_exp_f32_e32 v77, v77
	v_mul_f32_e32 v82, 0xbfb8aa3b, v79
	v_exp_f32_e32 v82, v82
	v_mul_f32_e32 v69, v69, v76
	v_add_f32_e32 v76, 1.0, v77
	v_rcp_f32_e32 v76, v76
	v_lshl_add_u64 v[96:97], v[96:97], 0, v[148:149]
	v_add_f32_e32 v77, 1.0, v82
	global_store_dwordx4 v[96:97], v[84:87], off sc0 sc1
	v_rcp_f32_e32 v77, v77
	v_cvt_pk_bf16_f32 v68, v68, v69
	v_mul_f32_e32 v69, v78, v76
	v_mul_f32_e32 v76, 0xbfb8aa3b, v72
	v_exp_f32_e32 v76, v76
	v_mul_f32_e32 v69, v70, v69
	v_mul_f32_e32 v70, v79, v77
	v_mul_f32_e32 v77, 0xbfb8aa3b, v73
	v_exp_f32_e32 v77, v77
	v_mul_f32_e32 v70, v71, v70
	v_add_f32_e32 v71, 1.0, v76
	v_rcp_f32_e32 v71, v71
	v_add_f32_e32 v76, 1.0, v77
	v_rcp_f32_e32 v76, v76
	v_cvt_pk_bf16_f32 v69, v69, v70
	v_mul_f32_e32 v70, v72, v71
	v_mul_f32_e32 v71, 0xbfb8aa3b, v74
	v_exp_f32_e32 v71, v71
	v_mul_f32_e32 v72, 0xbfb8aa3b, v75
	v_exp_f32_e32 v72, v72
	v_mul_f32_e32 v64, v64, v70
	v_mul_f32_e32 v70, v73, v76
	v_mul_f32_e32 v65, v65, v70
	v_add_f32_e32 v70, 1.0, v71
	v_rcp_f32_e32 v71, v70
	v_add_f32_e32 v70, 1.0, v72
	v_rcp_f32_e32 v72, v70
	v_cvt_pk_bf16_f32 v70, v64, v65
	v_mul_f32_e32 v64, v74, v71
	v_mul_f32_e32 v64, v66, v64
	v_mul_f32_e32 v65, v75, v72
	v_mul_f32_e32 v65, v67, v65
	v_cvt_pk_bf16_f32 v71, v64, v65
	v_mul_f32_e32 v65, 0xbfb8aa3b, v60
	v_exp_f32_e32 v66, v65
	v_mul_f32_e32 v65, 0xbfb8aa3b, v61
	v_exp_f32_e32 v67, v65
	v_or_b32_e32 v80, 48, v156
	v_add_f32_e32 v66, 1.0, v66
	v_rcp_f32_e32 v66, v66
	v_add_f32_e32 v67, 1.0, v67
	v_rcp_f32_e32 v67, v67
	v_mad_i64_i32 v[80:81], s[6:7], v80, s53, v[146:147]
	v_mul_f32_e32 v60, v60, v66
	v_mul_f32_e32 v52, v52, v60
	v_mul_f32_e32 v60, v61, v67
	v_mul_f32_e32 v61, 0xbfb8aa3b, v62
	v_exp_f32_e32 v61, v61
	v_mul_f32_e32 v66, 0xbfb8aa3b, v63
	v_exp_f32_e32 v66, v66
	v_mul_f32_e32 v53, v53, v60
	v_add_f32_e32 v60, 1.0, v61
	v_rcp_f32_e32 v60, v60
	v_lshl_add_u64 v[80:81], v[80:81], 0, v[148:149]
	v_add_f32_e32 v61, 1.0, v66
	global_store_dwordx4 v[80:81], v[68:71], off sc0 sc1
	v_rcp_f32_e32 v61, v61
	v_cvt_pk_bf16_f32 v52, v52, v53
	v_mul_f32_e32 v53, v62, v60
	v_mul_f32_e32 v60, 0xbfb8aa3b, v56
	v_exp_f32_e32 v60, v60
	v_mul_f32_e32 v53, v54, v53
	v_mul_f32_e32 v54, v63, v61
	v_mul_f32_e32 v61, 0xbfb8aa3b, v57
	v_exp_f32_e32 v61, v61
	v_mul_f32_e32 v54, v55, v54
	v_add_f32_e32 v55, 1.0, v60
	v_rcp_f32_e32 v55, v55
	v_add_f32_e32 v60, 1.0, v61
	v_rcp_f32_e32 v60, v60
	v_cvt_pk_bf16_f32 v53, v53, v54
	v_mul_f32_e32 v54, v56, v55
	v_mul_f32_e32 v55, 0xbfb8aa3b, v58
	v_exp_f32_e32 v55, v55
	v_mul_f32_e32 v56, 0xbfb8aa3b, v59
	v_exp_f32_e32 v56, v56
	v_mul_f32_e32 v48, v48, v54
	v_mul_f32_e32 v54, v57, v60
	v_mul_f32_e32 v49, v49, v54
	v_add_f32_e32 v54, 1.0, v55
	v_rcp_f32_e32 v55, v54
	v_add_f32_e32 v54, 1.0, v56
	v_rcp_f32_e32 v56, v54
	v_cvt_pk_bf16_f32 v54, v48, v49
	v_mul_f32_e32 v48, v58, v55
	v_mul_f32_e32 v48, v50, v48
	v_mul_f32_e32 v49, v59, v56
	v_mul_f32_e32 v49, v51, v49
	v_cvt_pk_bf16_f32 v55, v48, v49
	v_mul_f32_e32 v49, 0xbfb8aa3b, v44
	v_exp_f32_e32 v50, v49
	v_mul_f32_e32 v49, 0xbfb8aa3b, v45
	v_exp_f32_e32 v51, v49
	v_add_u32_e32 v64, 0x80, v156
	v_add_f32_e32 v50, 1.0, v50
	v_rcp_f32_e32 v50, v50
	v_add_f32_e32 v51, 1.0, v51
	v_rcp_f32_e32 v51, v51
	v_mad_i64_i32 v[64:65], s[6:7], v64, s53, v[146:147]
	v_mul_f32_e32 v44, v44, v50
	v_mul_f32_e32 v36, v36, v44
	v_mul_f32_e32 v44, v45, v51
	v_mul_f32_e32 v45, 0xbfb8aa3b, v46
	v_exp_f32_e32 v45, v45
	v_mul_f32_e32 v50, 0xbfb8aa3b, v47
	v_exp_f32_e32 v50, v50
	v_mul_f32_e32 v37, v37, v44
	v_add_f32_e32 v44, 1.0, v45
	v_rcp_f32_e32 v44, v44
	v_lshl_add_u64 v[64:65], v[64:65], 0, v[148:149]
	v_add_f32_e32 v45, 1.0, v50
	global_store_dwordx4 v[64:65], v[52:55], off sc0 sc1
	v_rcp_f32_e32 v45, v45
	v_cvt_pk_bf16_f32 v36, v36, v37
	v_mul_f32_e32 v37, v46, v44
	v_mul_f32_e32 v44, 0xbfb8aa3b, v40
	v_exp_f32_e32 v44, v44
	v_mul_f32_e32 v37, v38, v37
	v_mul_f32_e32 v38, v47, v45
	v_mul_f32_e32 v45, 0xbfb8aa3b, v41
	v_exp_f32_e32 v45, v45
	v_mul_f32_e32 v38, v39, v38
	v_add_f32_e32 v39, 1.0, v44
	v_rcp_f32_e32 v39, v39
	v_add_f32_e32 v44, 1.0, v45
	v_rcp_f32_e32 v44, v44
	v_cvt_pk_bf16_f32 v37, v37, v38
	v_mul_f32_e32 v38, v40, v39
	v_mul_f32_e32 v39, 0xbfb8aa3b, v42
	v_exp_f32_e32 v39, v39
	v_mul_f32_e32 v40, 0xbfb8aa3b, v43
	v_exp_f32_e32 v40, v40
	v_mul_f32_e32 v32, v32, v38
	v_mul_f32_e32 v38, v41, v44
	v_mul_f32_e32 v33, v33, v38
	v_add_f32_e32 v38, 1.0, v39
	v_rcp_f32_e32 v39, v38
	v_add_f32_e32 v38, 1.0, v40
	v_rcp_f32_e32 v40, v38
	v_cvt_pk_bf16_f32 v38, v32, v33
	v_mul_f32_e32 v32, v42, v39
	v_mul_f32_e32 v32, v34, v32
	v_mul_f32_e32 v33, v43, v40
	v_mul_f32_e32 v33, v35, v33
	v_cvt_pk_bf16_f32 v39, v32, v33
	v_mul_f32_e32 v33, 0xbfb8aa3b, v28
	v_exp_f32_e32 v34, v33
	v_mul_f32_e32 v33, 0xbfb8aa3b, v29
	v_exp_f32_e32 v35, v33
	v_add_u32_e32 v48, 0x90, v156
	v_add_f32_e32 v34, 1.0, v34
	v_rcp_f32_e32 v34, v34
	v_add_f32_e32 v35, 1.0, v35
	v_rcp_f32_e32 v35, v35
	v_mad_i64_i32 v[48:49], s[6:7], v48, s53, v[146:147]
	v_mul_f32_e32 v28, v28, v34
	v_mul_f32_e32 v20, v20, v28
	v_mul_f32_e32 v28, v29, v35
	v_mul_f32_e32 v29, 0xbfb8aa3b, v30
	v_exp_f32_e32 v29, v29
	v_mul_f32_e32 v34, 0xbfb8aa3b, v31
	v_exp_f32_e32 v34, v34
	v_mul_f32_e32 v21, v21, v28
	v_add_f32_e32 v28, 1.0, v29
	v_rcp_f32_e32 v28, v28
	v_lshl_add_u64 v[48:49], v[48:49], 0, v[148:149]
	v_add_f32_e32 v29, 1.0, v34
	global_store_dwordx4 v[48:49], v[36:39], off sc0 sc1
	v_rcp_f32_e32 v29, v29
	v_cvt_pk_bf16_f32 v20, v20, v21
	v_mul_f32_e32 v21, v30, v28
	v_mul_f32_e32 v28, 0xbfb8aa3b, v24
	v_exp_f32_e32 v28, v28
	v_mul_f32_e32 v21, v22, v21
	v_mul_f32_e32 v22, v31, v29
	v_mul_f32_e32 v29, 0xbfb8aa3b, v25
	v_exp_f32_e32 v29, v29
	v_mul_f32_e32 v22, v23, v22
	v_add_f32_e32 v23, 1.0, v28
	v_rcp_f32_e32 v23, v23
	v_add_f32_e32 v28, 1.0, v29
	v_rcp_f32_e32 v28, v28
	v_cvt_pk_bf16_f32 v21, v21, v22
	v_mul_f32_e32 v22, v24, v23
	v_mul_f32_e32 v23, 0xbfb8aa3b, v26
	v_exp_f32_e32 v23, v23
	v_mul_f32_e32 v24, 0xbfb8aa3b, v27
	v_exp_f32_e32 v24, v24
	v_mul_f32_e32 v16, v16, v22
	v_mul_f32_e32 v22, v25, v28
	v_mul_f32_e32 v17, v17, v22
	v_add_f32_e32 v22, 1.0, v23
	v_rcp_f32_e32 v23, v22
	v_add_f32_e32 v22, 1.0, v24
	v_rcp_f32_e32 v24, v22
	v_cvt_pk_bf16_f32 v22, v16, v17
	v_mul_f32_e32 v16, v26, v23
	v_mul_f32_e32 v16, v18, v16
	v_mul_f32_e32 v17, v27, v24
	v_mul_f32_e32 v17, v19, v17
	v_cvt_pk_bf16_f32 v23, v16, v17
	v_mul_f32_e32 v17, 0xbfb8aa3b, v12
	v_exp_f32_e32 v18, v17
	v_mul_f32_e32 v17, 0xbfb8aa3b, v13
	v_exp_f32_e32 v19, v17
	v_add_u32_e32 v32, 0xa0, v156
	v_add_f32_e32 v18, 1.0, v18
	v_rcp_f32_e32 v18, v18
	v_add_f32_e32 v19, 1.0, v19
	v_rcp_f32_e32 v19, v19
	v_mad_i64_i32 v[32:33], s[6:7], v32, s53, v[146:147]
	v_mul_f32_e32 v12, v12, v18
	v_mul_f32_e32 v4, v4, v12
	v_mul_f32_e32 v12, v13, v19
	v_mul_f32_e32 v13, 0xbfb8aa3b, v14
	v_exp_f32_e32 v13, v13
	v_mul_f32_e32 v18, 0xbfb8aa3b, v15
	v_exp_f32_e32 v18, v18
	v_mul_f32_e32 v5, v5, v12
	v_add_f32_e32 v12, 1.0, v13
	v_rcp_f32_e32 v12, v12
	v_lshl_add_u64 v[32:33], v[32:33], 0, v[148:149]
	v_add_f32_e32 v13, 1.0, v18
	global_store_dwordx4 v[32:33], v[20:23], off sc0 sc1
	v_rcp_f32_e32 v13, v13
	v_cvt_pk_bf16_f32 v4, v4, v5
	v_mul_f32_e32 v5, v14, v12
	v_mul_f32_e32 v12, 0xbfb8aa3b, v8
	v_exp_f32_e32 v12, v12
	v_mul_f32_e32 v5, v6, v5
	v_mul_f32_e32 v6, v15, v13
	v_mul_f32_e32 v13, 0xbfb8aa3b, v9
	v_exp_f32_e32 v13, v13
	v_mul_f32_e32 v6, v7, v6
	v_add_f32_e32 v7, 1.0, v12
	v_rcp_f32_e32 v7, v7
	v_add_f32_e32 v12, 1.0, v13
	v_rcp_f32_e32 v12, v12
	v_cvt_pk_bf16_f32 v5, v5, v6
	v_mul_f32_e32 v6, v8, v7
	v_mul_f32_e32 v7, 0xbfb8aa3b, v10
	v_exp_f32_e32 v7, v7
	v_mul_f32_e32 v8, 0xbfb8aa3b, v11
	v_exp_f32_e32 v8, v8
	v_mul_f32_e32 v0, v0, v6
	v_mul_f32_e32 v6, v9, v12
	v_mul_f32_e32 v1, v1, v6
	v_add_f32_e32 v6, 1.0, v7
	v_rcp_f32_e32 v7, v6
	v_add_f32_e32 v6, 1.0, v8
	v_rcp_f32_e32 v8, v6
	v_add_u32_e32 v16, 0xb0, v156
	v_mad_i64_i32 v[16:17], s[6:7], v16, s53, v[146:147]
	v_lshl_add_u64 v[16:17], v[16:17], 0, v[148:149]
	v_cvt_pk_bf16_f32 v6, v0, v1
	v_mul_f32_e32 v0, v10, v7
	v_mul_f32_e32 v1, v11, v8
	s_andn2_b64 vcc, exec, s[0:1]
	s_mov_b64 s[0:1], -1
	v_mul_f32_e32 v0, v2, v0
	v_mul_f32_e32 v1, v3, v1
	v_cvt_pk_bf16_f32 v7, v0, v1
	global_store_dwordx4 v[16:17], v[4:7], off sc0 sc1
	s_cbranch_vccnz .LBB0_1215
	s_andn2_b64 vcc, exec, s[8:9]
	s_cbranch_vccnz .LBB0_1214
	s_barrier
	s_branch .LBB0_1214
